# eight s_nop dwords ahead of the P1 main-loop header (instruction placement of the 8-phase loop; 2-3 us in quick timings)
# baseline (speedup 1.0000x reference)
; DEV int otid() { int t = threadIdx.x; asm volatile("" : "+v"(t)); return t; }
; #define STAGE(P, BASE, br, kt) do { const char* _gb = (const char*)(BASE) + (((long)(br) * K + (long)(kt) * BK) << 1); \
;     __builtin_amdgcn_global_load_lds((const unsigned*)(_gb + so0), (unsigned*)((char*)(P) + tb), 16, 0, 0); \
;     __builtin_amdgcn_global_load_lds((const unsigned*)(_gb + so1), (unsigned*)((char*)(P) + tb + 8192), 16, 0, 0); } while (0)
; #define WAIT_V(n) asm volatile("s_waitcnt vmcnt(" #n ")" ::: "memory")
; #define BAR __builtin_amdgcn_s_barrier()
; template <bool SWAP, class Epi>
; DEV void gemm_tile(const bf16_t* __restrict__ A, const bf16_t* __restrict__ Bt, const int K, const int brow, const int bcol, const Epi& epi) {
;     ...
;   const int tidx = otid();
;   const int wid = tidx >> 6, lane = tidx & 63, wr = wid >> 2, wc = wid & 3, fr = lane & 15, fq = lane >> 4;
;   f32x4 acc[2][2][4][2] = {};
;   bf16x8 At[4][2], B0[2][2], B1[2][2];
;   const int nt = K / BK;
;   const int tb = tidx * 16;
;   unsigned so0, so1;
;   { int r_, c_; stage_rc(tb, r_, c_); so0 = (unsigned)(r_ * K + c_) * 2u; stage_rc(tb + 8192, r_, c_); so1 = (unsigned)(r_ * K + c_) * 2u; }
;   const int tb16 = (fr * 64 + fq * 16) ^ ((fr >> 3) << 5);
;   const int a_rd = wr * 8192 + tb16, b_rd = wc * 4096 + tb16;
;   WAIT_V(0);
;   __syncthreads();
;   STAGE(SB(0, 0), Bt, bcol, 0); STAGE(SA(0, 0), A, brow, 0);
;   STAGE(SB(0, 1), Bt, bcol + HALF, 0); STAGE(SA(0, 1), A, brow + HALF, 0);
;   if (wr == 1) BAR;
;   WAIT_V(4); BAR;
;   STAGE(SB(1, 0), Bt, bcol, 1); STAGE(SA(1, 0), A, brow, 1); STAGE(SB(1, 1), Bt, bcol + HALF, 1);
;   WAIT_V(6); BAR;
; #pragma unroll 1
;   for (int t = 0; t < nt - 2; t += 2) {
.Lp1d_w6d_a:
	v_lshl_add_u32 v0, v8, 1, v0
	v_mov_b32_e32 v1, v177
	v_lshl_add_u64 v[134:135], s[20:21], 0, v[0:1]
	v_lshl_add_u64 v[138:139], s[18:19], 0, v[0:1]
	v_mov_b32_e32 v0, 0
	s_xor_b64 s[16:17], s[16:17], -1
	v_lshl_add_u64 v[132:133], s[20:21], 0, v[176:177]
	v_lshl_add_u64 v[136:137], s[18:19], 0, v[176:177]
	s_mov_b32 s5, -2
	v_add_u32_e32 v140, 0, v9
	s_mov_b64 s[18:19], s[62:63]
	v_mov_b32_e32 v1, v0
	v_mov_b32_e32 v2, v0
	v_mov_b32_e32 v3, v0
	v_mov_b32_e32 v4, v0
	v_mov_b32_e32 v5, v0
	v_mov_b32_e32 v6, v0
	v_mov_b32_e32 v7, v0
	v_mov_b32_e32 v8, v0
	v_mov_b32_e32 v9, v0
	v_mov_b32_e32 v10, v0
	v_mov_b32_e32 v11, v0
	v_mov_b32_e32 v12, v0
	v_mov_b32_e32 v13, v0
	v_mov_b32_e32 v14, v0
	v_mov_b32_e32 v15, v0
	v_mov_b32_e32 v16, v0
	v_mov_b32_e32 v17, v0
	v_mov_b32_e32 v18, v0
	v_mov_b32_e32 v19, v0
	v_mov_b32_e32 v20, v0
	v_mov_b32_e32 v21, v0
	v_mov_b32_e32 v22, v0
	v_mov_b32_e32 v23, v0
	v_mov_b32_e32 v24, v0
	v_mov_b32_e32 v25, v0
	v_mov_b32_e32 v26, v0
	v_mov_b32_e32 v27, v0
	v_mov_b32_e32 v28, v0
	v_mov_b32_e32 v29, v0
	v_mov_b32_e32 v30, v0
	v_mov_b32_e32 v31, v0
	v_mov_b32_e32 v32, v0
	v_mov_b32_e32 v33, v0
	v_mov_b32_e32 v34, v0
	v_mov_b32_e32 v35, v0
	v_mov_b32_e32 v36, v0
	v_mov_b32_e32 v37, v0
	v_mov_b32_e32 v38, v0
	v_mov_b32_e32 v39, v0
	v_mov_b32_e32 v40, v0
	v_mov_b32_e32 v41, v0
	v_mov_b32_e32 v42, v0
	v_mov_b32_e32 v43, v0
	v_mov_b32_e32 v44, v0
	v_mov_b32_e32 v45, v0
	v_mov_b32_e32 v46, v0
	v_mov_b32_e32 v47, v0
	v_mov_b32_e32 v48, v0
	v_mov_b32_e32 v49, v0
	v_mov_b32_e32 v50, v0
	v_mov_b32_e32 v51, v0
	v_mov_b32_e32 v52, v0
	v_mov_b32_e32 v53, v0
	v_mov_b32_e32 v54, v0
	v_mov_b32_e32 v55, v0
	v_mov_b32_e32 v56, v0
	v_mov_b32_e32 v57, v0
	v_mov_b32_e32 v58, v0
	v_mov_b32_e32 v59, v0
	v_mov_b32_e32 v60, v0
	v_mov_b32_e32 v61, v0
	v_mov_b32_e32 v62, v0
	v_mov_b32_e32 v63, v0
	v_mov_b32_e32 v64, v0
	v_mov_b32_e32 v65, v0
	v_mov_b32_e32 v66, v0
	v_mov_b32_e32 v67, v0
	v_mov_b32_e32 v68, v0
	v_mov_b32_e32 v69, v0
	v_mov_b32_e32 v70, v0
	v_mov_b32_e32 v71, v0
	v_mov_b32_e32 v72, v0
	v_mov_b32_e32 v73, v0
	v_mov_b32_e32 v74, v0
	v_mov_b32_e32 v75, v0
	v_mov_b32_e32 v76, v0
	v_mov_b32_e32 v77, v0
	v_mov_b32_e32 v78, v0
	v_mov_b32_e32 v79, v0
	v_mov_b32_e32 v80, v0
	v_mov_b32_e32 v81, v0
	v_mov_b32_e32 v82, v0
	v_mov_b32_e32 v83, v0
	v_mov_b32_e32 v84, v0
	v_mov_b32_e32 v85, v0
	v_mov_b32_e32 v86, v0
	v_mov_b32_e32 v87, v0
	v_mov_b32_e32 v88, v0
	v_mov_b32_e32 v89, v0
	v_mov_b32_e32 v90, v0
	v_mov_b32_e32 v91, v0
	v_mov_b32_e32 v92, v0
	v_mov_b32_e32 v93, v0
	v_mov_b32_e32 v94, v0
	v_mov_b32_e32 v95, v0
	v_mov_b32_e32 v96, v0
	v_mov_b32_e32 v97, v0
	v_mov_b32_e32 v98, v0
	v_mov_b32_e32 v99, v0
	v_mov_b32_e32 v100, v0
	v_mov_b32_e32 v101, v0
	v_mov_b32_e32 v102, v0
	v_mov_b32_e32 v103, v0
	v_mov_b32_e32 v104, v0
	v_mov_b32_e32 v105, v0
	v_mov_b32_e32 v106, v0
	v_mov_b32_e32 v107, v0
	v_mov_b32_e32 v108, v0
	v_mov_b32_e32 v109, v0
	v_mov_b32_e32 v110, v0
	v_mov_b32_e32 v111, v0
	v_mov_b32_e32 v112, v0
	v_mov_b32_e32 v113, v0
	v_mov_b32_e32 v114, v0
	v_mov_b32_e32 v115, v0
	v_mov_b32_e32 v116, v0
	v_mov_b32_e32 v117, v0
	v_mov_b32_e32 v118, v0
	v_mov_b32_e32 v119, v0
	v_mov_b32_e32 v120, v0
	v_mov_b32_e32 v121, v0
	v_mov_b32_e32 v122, v0
	v_mov_b32_e32 v123, v0
	v_mov_b32_e32 v124, v0
	v_mov_b32_e32 v125, v0
	v_mov_b32_e32 v126, v0
	v_mov_b32_e32 v127, v0
	s_mov_b64 s[20:21], 0x8800100
	s_mov_b64 s[22:23], 0x8880080
	s_mov_b64 s[24:25], 0x8880100
	s_mov_b64 s[26:27], 0x8800180
	s_barrier
	s_nop 0
	s_nop 0
	s_nop 0
	s_nop 0
	s_nop 0
	s_nop 0
	s_nop 0
	s_nop 0
